# local barriers: L1 invalidate issued at arrival (overlaps the wait for the other workgroups), slot-store barrier form
# baseline (speedup 1.0000x reference)
.LBB0_347:
	s_and_b64 vcc, exec, s[0:1]
	s_cbranch_vccz .LBB0_367
	s_waitcnt vmcnt(0)
	s_waitcnt vmcnt(0)
	s_barrier
	s_mov_b64 s[0:1], exec
	v_readlane_b32 s2, v252, 8
	v_readlane_b32 s3, v252, 9
	s_and_b64 s[2:3], s[0:1], s[2:3]
	s_mov_b64 exec, s[2:3]
	s_cbranch_execz .LBB0_366
	s_add_i32 s100, s100, 1
	v_mov_b32_e32 v1, 0x20000
	s_waitcnt vmcnt(0) expcnt(0) lgkmcnt(0)
	ds_read2_b32 v[2:3], v1 offset1:3
	v_readlane_b32 s2, v252, 7
	s_lshl_b32 s2, s2, 8
	v_readlane_b32 s6, v252, 5
	v_readlane_b32 s7, v252, 6
	s_add_u32 s2, s6, s2
	s_addc_u32 s3, s7, 0
	v_mov_b32_e32 v4, s100
	s_waitcnt lgkmcnt(0)
	v_readfirstlane_b32 s4, v2
	v_lshlrev_b32_e32 v3, 2, v3
	v_add_u32_e32 v3, 0x3000, v3
	global_store_dword v3, v4, s[2:3] offset:1536
	buffer_inv sc1
	s_bfm_b64 exec, s4, 0
	v_mbcnt_lo_u32_b32 v5, -1, 0
	v_mbcnt_hi_u32_b32 v5, -1, v5
	v_lshlrev_b32_e32 v5, 2, v5
	v_add_u32_e32 v5, 0x3000, v5
	s_mov_b32 s101, 0

my_lb_done_5:
	s_waitcnt vmcnt(0)

my_lb_done_4:
	s_waitcnt vmcnt(0)

my_lb_done_3:
	s_waitcnt vmcnt(0)

my_lb_done_2:
	s_waitcnt vmcnt(0)

my_lb_done_1:
	s_waitcnt vmcnt(0)

.LBB0_1345:
	s_and_b64 vcc, exec, s[0:1]
	s_cbranch_vccz .LBB0_1365
	s_waitcnt vmcnt(0)
	s_waitcnt vmcnt(0) lgkmcnt(0)
	s_barrier
	s_mov_b64 s[0:1], exec
	v_readlane_b32 s2, v252, 8
	v_readlane_b32 s3, v252, 9
	s_and_b64 s[2:3], s[0:1], s[2:3]
	s_mov_b64 exec, s[2:3]
	s_cbranch_execz .LBB0_1364
	s_add_i32 s100, s100, 1
	v_mov_b32_e32 v1, 0x20000
	s_waitcnt vmcnt(0) expcnt(0) lgkmcnt(0)
	ds_read2_b32 v[2:3], v1 offset1:3
	v_readlane_b32 s2, v252, 7
	s_lshl_b32 s2, s2, 8
	v_readlane_b32 s6, v252, 5
	v_readlane_b32 s7, v252, 6
	s_add_u32 s2, s6, s2
	s_addc_u32 s3, s7, 0
	v_mov_b32_e32 v4, s100
	s_waitcnt lgkmcnt(0)
	v_readfirstlane_b32 s4, v2
	v_lshlrev_b32_e32 v3, 2, v3
	v_add_u32_e32 v3, 0x3000, v3
	global_store_dword v3, v4, s[2:3] offset:1536
	buffer_inv sc1
	s_bfm_b64 exec, s4, 0
	v_mbcnt_lo_u32_b32 v5, -1, 0
	v_mbcnt_hi_u32_b32 v5, -1, v5
	v_lshlrev_b32_e32 v5, 2, v5
	v_add_u32_e32 v5, 0x3000, v5
	s_mov_b32 s101, 0

my_lb_done_0:
	s_waitcnt vmcnt(0)
